# late MFMA-opening barrier (after 4 MFMAs) also in super-phase 3 of the peeled first K-tile pair, on top of v57
# speedup vs baseline: 1.0093x; 1.0026x over previous
.LBB0_227:
	s_waitcnt lgkmcnt(0)
	s_add_i32 s18, s58, 0x180
	s_add_i32 s19, s57, 0x180
	s_setprio 1
	s_waitcnt lgkmcnt(7)
	v_mfma_f32_16x16x32_bf16 v[114:117], v[146:149], v[186:189], v[114:117]
	v_mfma_f32_16x16x32_bf16 v[110:113], v[154:157], v[186:189], v[110:113]
	s_waitcnt lgkmcnt(6)
	v_mfma_f32_16x16x32_bf16 v[106:109], v[146:149], v[174:177], v[106:109]
	v_mfma_f32_16x16x32_bf16 v[102:105], v[154:157], v[174:177], v[102:105]
	s_barrier
	s_waitcnt lgkmcnt(3)
	v_mfma_f32_16x16x32_bf16 v[98:101], v[146:149], v[170:173], v[98:101]
	v_mfma_f32_16x16x32_bf16 v[94:97], v[154:157], v[170:173], v[94:97]
	s_waitcnt lgkmcnt(2)
	v_mfma_f32_16x16x32_bf16 v[90:93], v[146:149], v[162:165], v[90:93]
	v_mfma_f32_16x16x32_bf16 v[86:89], v[154:157], v[162:165], v[86:89]
	v_mfma_f32_16x16x32_bf16 v[114:117], v[150:153], v[190:193], v[114:117]
	v_mfma_f32_16x16x32_bf16 v[110:113], v[158:161], v[190:193], v[110:113]
	v_mfma_f32_16x16x32_bf16 v[106:109], v[150:153], v[178:181], v[106:109]
	v_mfma_f32_16x16x32_bf16 v[102:105], v[158:161], v[178:181], v[102:105]
	s_waitcnt lgkmcnt(1)
	v_mfma_f32_16x16x32_bf16 v[98:101], v[150:153], v[182:185], v[98:101]
	v_mfma_f32_16x16x32_bf16 v[94:97], v[158:161], v[182:185], v[94:97]
	s_waitcnt lgkmcnt(0)
	v_mfma_f32_16x16x32_bf16 v[90:93], v[150:153], v[166:169], v[90:93]
	v_mfma_f32_16x16x32_bf16 v[86:89], v[158:161], v[166:169], v[86:89]
	s_setprio 0
	s_setprio 1
	v_mfma_f32_16x16x32_bf16 v[82:85], v[130:133], v[186:189], v[82:85]
	v_mfma_f32_16x16x32_bf16 v[74:77], v[138:141], v[186:189], v[74:77]
	v_mfma_f32_16x16x32_bf16 v[70:73], v[130:133], v[174:177], v[70:73]
	v_mfma_f32_16x16x32_bf16 v[66:69], v[138:141], v[174:177], v[66:69]
	v_mfma_f32_16x16x32_bf16 v[62:65], v[130:133], v[170:173], v[62:65]
	v_mfma_f32_16x16x32_bf16 v[58:61], v[138:141], v[170:173], v[58:61]
	v_mfma_f32_16x16x32_bf16 v[54:57], v[130:133], v[162:165], v[54:57]
	v_mfma_f32_16x16x32_bf16 v[50:53], v[138:141], v[162:165], v[50:53]
	v_mfma_f32_16x16x32_bf16 v[82:85], v[134:137], v[190:193], v[82:85]
	v_mfma_f32_16x16x32_bf16 v[74:77], v[142:145], v[190:193], v[74:77]
	v_mfma_f32_16x16x32_bf16 v[70:73], v[134:137], v[178:181], v[70:73]
	v_mfma_f32_16x16x32_bf16 v[66:69], v[142:145], v[178:181], v[66:69]
	v_mfma_f32_16x16x32_bf16 v[62:65], v[134:137], v[182:185], v[62:65]
	v_mfma_f32_16x16x32_bf16 v[58:61], v[142:145], v[182:185], v[58:61]
	v_mfma_f32_16x16x32_bf16 v[54:57], v[134:137], v[166:169], v[54:57]
	v_mfma_f32_16x16x32_bf16 v[50:53], v[142:145], v[166:169], v[50:53]
	s_setprio 0
	s_barrier
	s_mov_b32 m0, s29
	s_mov_b32 s4, s70
	ds_read_b128 v[186:189], v221 offset:49152
	ds_read_b128 v[174:177], v221 offset:51200
	ds_read_b128 v[190:193], v222 offset:49152
	ds_read_b128 v[178:181], v222 offset:51200
	ds_read_b128 v[170:173], v221 offset:53248
	ds_read_b128 v[162:165], v221 offset:55296
	ds_read_b128 v[182:185], v222 offset:53248
	ds_read_b128 v[166:169], v222 offset:55296
	buffer_load_dwordx4 v208, s[4:7], s19 offen lds
	s_mov_b32 m0, s30
	s_and_b64 vcc, exec, s[2:3]
	buffer_load_dwordx4 v210, s[4:7], s19 offen lds
	s_add_i32 s19, s57, 0x40180
	s_mov_b32 m0, s35
	s_nop 0
	buffer_load_dwordx4 v208, s[4:7], s19 offen lds
	s_mov_b32 m0, s36
	s_nop 0
	buffer_load_dwordx4 v210, s[4:7], s19 offen lds
	s_mov_b32 m0, s31
	s_nop 0
	buffer_load_dwordx4 v207, s[4:7], s18 offen lds
	s_mov_b32 m0, s34
	s_nop 0
	buffer_load_dwordx4 v209, s[4:7], s18 offen lds
	s_cbranch_vccnz .LBB0_252
	s_waitcnt vmcnt(22)
	s_cbranch_execnz .LBB0_230

.LBB0_536:
	s_waitcnt lgkmcnt(0)
	s_add_i32 s62, s55, 0x180
	s_add_i32 s22, s61, 0x180
	s_setprio 1
	s_waitcnt lgkmcnt(7)
	v_mfma_f32_16x16x32_bf16 v[126:129], v[146:149], v[186:189], v[126:129]
	v_mfma_f32_16x16x32_bf16 v[122:125], v[154:157], v[186:189], v[122:125]
	s_waitcnt lgkmcnt(6)
	v_mfma_f32_16x16x32_bf16 v[118:121], v[146:149], v[174:177], v[118:121]
	v_mfma_f32_16x16x32_bf16 v[114:117], v[154:157], v[174:177], v[114:117]
	s_barrier
	s_waitcnt lgkmcnt(3)
	v_mfma_f32_16x16x32_bf16 v[110:113], v[146:149], v[170:173], v[110:113]
	v_mfma_f32_16x16x32_bf16 v[106:109], v[154:157], v[170:173], v[106:109]
	s_waitcnt lgkmcnt(2)
	v_mfma_f32_16x16x32_bf16 v[102:105], v[146:149], v[162:165], v[102:105]
	v_mfma_f32_16x16x32_bf16 v[98:101], v[154:157], v[162:165], v[98:101]
	v_mfma_f32_16x16x32_bf16 v[126:129], v[150:153], v[190:193], v[126:129]
	v_mfma_f32_16x16x32_bf16 v[122:125], v[158:161], v[190:193], v[122:125]
	v_mfma_f32_16x16x32_bf16 v[118:121], v[150:153], v[178:181], v[118:121]
	v_mfma_f32_16x16x32_bf16 v[114:117], v[158:161], v[178:181], v[114:117]
	s_waitcnt lgkmcnt(1)
	v_mfma_f32_16x16x32_bf16 v[110:113], v[150:153], v[182:185], v[110:113]
	v_mfma_f32_16x16x32_bf16 v[106:109], v[158:161], v[182:185], v[106:109]
	s_waitcnt lgkmcnt(0)
	v_mfma_f32_16x16x32_bf16 v[102:105], v[150:153], v[166:169], v[102:105]
	v_mfma_f32_16x16x32_bf16 v[98:101], v[158:161], v[166:169], v[98:101]
	s_setprio 0
	s_setprio 1
	v_mfma_f32_16x16x32_bf16 v[94:97], v[130:133], v[186:189], v[94:97]
	v_mfma_f32_16x16x32_bf16 v[90:93], v[138:141], v[186:189], v[90:93]
	v_mfma_f32_16x16x32_bf16 v[86:89], v[130:133], v[174:177], v[86:89]
	v_mfma_f32_16x16x32_bf16 v[82:85], v[138:141], v[174:177], v[82:85]
	v_mfma_f32_16x16x32_bf16 v[78:81], v[130:133], v[170:173], v[78:81]
	v_mfma_f32_16x16x32_bf16 v[74:77], v[138:141], v[170:173], v[74:77]
	v_mfma_f32_16x16x32_bf16 v[70:73], v[130:133], v[162:165], v[70:73]
	v_mfma_f32_16x16x32_bf16 v[66:69], v[138:141], v[162:165], v[66:69]
	v_mfma_f32_16x16x32_bf16 v[94:97], v[134:137], v[190:193], v[94:97]
	v_mfma_f32_16x16x32_bf16 v[90:93], v[142:145], v[190:193], v[90:93]
	v_mfma_f32_16x16x32_bf16 v[86:89], v[134:137], v[178:181], v[86:89]
	v_mfma_f32_16x16x32_bf16 v[82:85], v[142:145], v[178:181], v[82:85]
	v_mfma_f32_16x16x32_bf16 v[78:81], v[134:137], v[182:185], v[78:81]
	v_mfma_f32_16x16x32_bf16 v[74:77], v[142:145], v[182:185], v[74:77]
	v_mfma_f32_16x16x32_bf16 v[70:73], v[134:137], v[166:169], v[70:73]
	v_mfma_f32_16x16x32_bf16 v[66:69], v[142:145], v[166:169], v[66:69]
	s_setprio 0
	s_barrier
	s_mov_b32 m0, s36
	s_mov_b32 s4, s70
	ds_read_b128 v[186:189], v219 offset:49152
	ds_read_b128 v[174:177], v219 offset:51200
	ds_read_b128 v[190:193], v220 offset:49152
	ds_read_b128 v[178:181], v220 offset:51200
	ds_read_b128 v[170:173], v219 offset:53248
	ds_read_b128 v[162:165], v219 offset:55296
	ds_read_b128 v[182:185], v220 offset:53248
	ds_read_b128 v[166:169], v220 offset:55296
	buffer_load_dwordx4 v233, s[4:7], s22 offen lds
	s_mov_b32 m0, s37
	s_and_b64 vcc, exec, s[2:3]
	buffer_load_dwordx4 v234, s[4:7], s22 offen lds
	s_add_i32 s22, s22, s60
	s_mov_b32 m0, s40
	s_nop 0
	buffer_load_dwordx4 v233, s[4:7], s22 offen lds
	s_mov_b32 m0, s41
	s_nop 0
	buffer_load_dwordx4 v234, s[4:7], s22 offen lds
	s_mov_b32 m0, s38
	s_nop 0
	buffer_load_dwordx4 v194, s[4:7], s62 offen lds
	s_mov_b32 m0, s39
	s_nop 0
	buffer_load_dwordx4 v222, s[4:7], s62 offen lds
	s_cbranch_vccnz .LBB0_559
	s_waitcnt vmcnt(22)
	s_cbranch_execnz .LBB0_539

.LBB0_830:
	s_waitcnt lgkmcnt(0)
	s_add_i32 s2, s42, 0x180
	s_add_i32 s3, s34, 0x180
	s_setprio 1
	s_waitcnt lgkmcnt(7)
	v_mfma_f32_16x16x32_bf16 v[74:77], v[146:149], v[186:189], v[74:77]
	v_mfma_f32_16x16x32_bf16 v[70:73], v[154:157], v[186:189], v[70:73]
	s_waitcnt lgkmcnt(6)
	v_mfma_f32_16x16x32_bf16 v[66:69], v[146:149], v[174:177], v[66:69]
	v_mfma_f32_16x16x32_bf16 v[82:85], v[154:157], v[174:177], v[82:85]
	s_barrier
	s_waitcnt lgkmcnt(3)
	v_mfma_f32_16x16x32_bf16 v[78:81], v[146:149], v[170:173], v[78:81]
	v_mfma_f32_16x16x32_bf16 v[90:93], v[154:157], v[170:173], v[90:93]
	s_waitcnt lgkmcnt(2)
	v_mfma_f32_16x16x32_bf16 v[86:89], v[146:149], v[162:165], v[86:89]
	v_mfma_f32_16x16x32_bf16 v[102:105], v[154:157], v[162:165], v[102:105]
	v_mfma_f32_16x16x32_bf16 v[74:77], v[150:153], v[190:193], v[74:77]
	v_mfma_f32_16x16x32_bf16 v[70:73], v[158:161], v[190:193], v[70:73]
	v_mfma_f32_16x16x32_bf16 v[66:69], v[150:153], v[178:181], v[66:69]
	v_mfma_f32_16x16x32_bf16 v[82:85], v[158:161], v[178:181], v[82:85]
	s_waitcnt lgkmcnt(1)
	v_mfma_f32_16x16x32_bf16 v[78:81], v[150:153], v[182:185], v[78:81]
	v_mfma_f32_16x16x32_bf16 v[90:93], v[158:161], v[182:185], v[90:93]
	s_waitcnt lgkmcnt(0)
	v_mfma_f32_16x16x32_bf16 v[86:89], v[150:153], v[166:169], v[86:89]
	v_mfma_f32_16x16x32_bf16 v[102:105], v[158:161], v[166:169], v[102:105]
	s_setprio 0
	s_setprio 1
	v_mfma_f32_16x16x32_bf16 v[98:101], v[130:133], v[186:189], v[98:101]
	v_mfma_f32_16x16x32_bf16 v[94:97], v[138:141], v[186:189], v[94:97]
	v_mfma_f32_16x16x32_bf16 v[106:109], v[130:133], v[174:177], v[106:109]
	v_mfma_f32_16x16x32_bf16 v[110:113], v[138:141], v[174:177], v[110:113]
	v_mfma_f32_16x16x32_bf16 v[114:117], v[130:133], v[170:173], v[114:117]
	v_mfma_f32_16x16x32_bf16 v[118:121], v[138:141], v[170:173], v[118:121]
	v_mfma_f32_16x16x32_bf16 v[122:125], v[130:133], v[162:165], v[122:125]
	v_mfma_f32_16x16x32_bf16 v[126:129], v[138:141], v[162:165], v[126:129]
	v_mfma_f32_16x16x32_bf16 v[98:101], v[134:137], v[190:193], v[98:101]
	v_mfma_f32_16x16x32_bf16 v[94:97], v[142:145], v[190:193], v[94:97]
	v_mfma_f32_16x16x32_bf16 v[106:109], v[134:137], v[178:181], v[106:109]
	v_mfma_f32_16x16x32_bf16 v[110:113], v[142:145], v[178:181], v[110:113]
	v_mfma_f32_16x16x32_bf16 v[114:117], v[134:137], v[182:185], v[114:117]
	v_mfma_f32_16x16x32_bf16 v[118:121], v[142:145], v[182:185], v[118:121]
	v_mfma_f32_16x16x32_bf16 v[122:125], v[134:137], v[166:169], v[122:125]
	v_mfma_f32_16x16x32_bf16 v[126:129], v[142:145], v[166:169], v[126:129]
	s_setprio 0
	s_barrier
	s_mov_b32 m0, s44
	s_mov_b32 s8, s70
	ds_read_b128 v[186:189], v248 offset:49152
	ds_read_b128 v[174:177], v248 offset:51200
	ds_read_b128 v[190:193], v249 offset:49152
	ds_read_b128 v[178:181], v249 offset:51200
	ds_read_b128 v[170:173], v248 offset:53248
	ds_read_b128 v[162:165], v248 offset:55296
	ds_read_b128 v[182:185], v249 offset:53248
	ds_read_b128 v[166:169], v249 offset:55296
	buffer_load_dwordx4 v233, s[8:11], s3 offen lds
	s_mov_b32 m0, s45
	s_and_b64 vcc, exec, s[0:1]
	buffer_load_dwordx4 v235, s[8:11], s3 offen lds
	s_add_i32 s3, s34, 0x40180
	s_mov_b32 m0, s48
	s_nop 0
	buffer_load_dwordx4 v233, s[8:11], s3 offen lds
	s_mov_b32 m0, s49
	s_nop 0
	buffer_load_dwordx4 v235, s[8:11], s3 offen lds
	s_mov_b32 m0, s46
	s_nop 0
	buffer_load_dwordx4 v1, s[8:11], s2 offen lds
	s_mov_b32 m0, s47
	s_nop 0
	buffer_load_dwordx4 v234, s[8:11], s2 offen lds
	s_mov_b64 s[2:3], -1
	s_cbranch_vccz .LBB0_832
	s_waitcnt vmcnt(8)
	s_mov_b64 s[2:3], 0

.LBB0_1111:
	s_waitcnt lgkmcnt(0)
	s_add_i32 s4, s31, 0x180
	s_add_i32 s5, s26, 0x180
	s_setprio 1
	s_waitcnt lgkmcnt(7)
	v_mfma_f32_16x16x32_bf16 v[126:129], v[146:149], v[186:189], v[126:129]
	v_mfma_f32_16x16x32_bf16 v[122:125], v[154:157], v[186:189], v[122:125]
	s_waitcnt lgkmcnt(6)
	v_mfma_f32_16x16x32_bf16 v[118:121], v[146:149], v[174:177], v[118:121]
	v_mfma_f32_16x16x32_bf16 v[114:117], v[154:157], v[174:177], v[114:117]
	s_barrier
	s_waitcnt lgkmcnt(3)
	v_mfma_f32_16x16x32_bf16 v[110:113], v[146:149], v[170:173], v[110:113]
	v_mfma_f32_16x16x32_bf16 v[106:109], v[154:157], v[170:173], v[106:109]
	s_waitcnt lgkmcnt(2)
	v_mfma_f32_16x16x32_bf16 v[102:105], v[146:149], v[162:165], v[102:105]
	v_mfma_f32_16x16x32_bf16 v[98:101], v[154:157], v[162:165], v[98:101]
	v_mfma_f32_16x16x32_bf16 v[126:129], v[150:153], v[190:193], v[126:129]
	v_mfma_f32_16x16x32_bf16 v[122:125], v[158:161], v[190:193], v[122:125]
	v_mfma_f32_16x16x32_bf16 v[118:121], v[150:153], v[178:181], v[118:121]
	v_mfma_f32_16x16x32_bf16 v[114:117], v[158:161], v[178:181], v[114:117]
	s_waitcnt lgkmcnt(1)
	v_mfma_f32_16x16x32_bf16 v[110:113], v[150:153], v[182:185], v[110:113]
	v_mfma_f32_16x16x32_bf16 v[106:109], v[158:161], v[182:185], v[106:109]
	s_waitcnt lgkmcnt(0)
	v_mfma_f32_16x16x32_bf16 v[102:105], v[150:153], v[166:169], v[102:105]
	v_mfma_f32_16x16x32_bf16 v[98:101], v[158:161], v[166:169], v[98:101]
	s_setprio 0
	s_setprio 1
	v_mfma_f32_16x16x32_bf16 v[94:97], v[130:133], v[186:189], v[94:97]
	v_mfma_f32_16x16x32_bf16 v[90:93], v[138:141], v[186:189], v[90:93]
	v_mfma_f32_16x16x32_bf16 v[86:89], v[130:133], v[174:177], v[86:89]
	v_mfma_f32_16x16x32_bf16 v[82:85], v[138:141], v[174:177], v[82:85]
	v_mfma_f32_16x16x32_bf16 v[78:81], v[130:133], v[170:173], v[78:81]
	v_mfma_f32_16x16x32_bf16 v[74:77], v[138:141], v[170:173], v[74:77]
	v_mfma_f32_16x16x32_bf16 v[70:73], v[130:133], v[162:165], v[70:73]
	v_mfma_f32_16x16x32_bf16 v[66:69], v[138:141], v[162:165], v[66:69]
	v_mfma_f32_16x16x32_bf16 v[94:97], v[134:137], v[190:193], v[94:97]
	v_mfma_f32_16x16x32_bf16 v[90:93], v[142:145], v[190:193], v[90:93]
	v_mfma_f32_16x16x32_bf16 v[86:89], v[134:137], v[178:181], v[86:89]
	v_mfma_f32_16x16x32_bf16 v[82:85], v[142:145], v[178:181], v[82:85]
	v_mfma_f32_16x16x32_bf16 v[78:81], v[134:137], v[182:185], v[78:81]
	v_mfma_f32_16x16x32_bf16 v[74:77], v[142:145], v[182:185], v[74:77]
	v_mfma_f32_16x16x32_bf16 v[70:73], v[134:137], v[166:169], v[70:73]
	v_mfma_f32_16x16x32_bf16 v[66:69], v[142:145], v[166:169], v[66:69]
	s_setprio 0
	s_barrier
	s_mov_b32 m0, s35
	ds_read_b128 v[186:189], v248 offset:49152
	ds_read_b128 v[174:177], v248 offset:51200
	ds_read_b128 v[190:193], v249 offset:49152
	ds_read_b128 v[178:181], v249 offset:51200
	ds_read_b128 v[170:173], v248 offset:53248
	ds_read_b128 v[162:165], v248 offset:55296
	ds_read_b128 v[182:185], v249 offset:53248
	ds_read_b128 v[166:169], v249 offset:55296
	buffer_load_dwordx4 v233, s[12:15], s5 offen lds
	s_mov_b32 m0, s36
	s_and_b64 vcc, exec, s[2:3]
	buffer_load_dwordx4 v235, s[12:15], s5 offen lds
	s_add_i32 s5, s26, 0x40180
	s_mov_b32 m0, s39
	s_nop 0
	buffer_load_dwordx4 v233, s[12:15], s5 offen lds
	s_mov_b32 m0, s41
	s_nop 0
	buffer_load_dwordx4 v235, s[12:15], s5 offen lds
	s_mov_b32 m0, s37
	s_nop 0
	buffer_load_dwordx4 v1, s[12:15], s4 offen lds
	s_mov_b32 m0, s38
	s_nop 0
	buffer_load_dwordx4 v234, s[12:15], s4 offen lds
	s_mov_b64 s[4:5], -1
	s_cbranch_vccz .LBB0_1113
	s_waitcnt vmcnt(8)
	s_mov_b64 s[4:5], 0

.LBB0_1240:
	s_waitcnt lgkmcnt(0)
	s_add_i32 s2, s51, 0x180
	s_add_i32 s3, s46, 0x180
	s_setprio 1
	s_waitcnt lgkmcnt(7)
	v_mfma_f32_16x16x32_bf16 v[74:77], v[146:149], v[186:189], v[74:77]
	v_mfma_f32_16x16x32_bf16 v[70:73], v[154:157], v[186:189], v[70:73]
	s_waitcnt lgkmcnt(6)
	v_mfma_f32_16x16x32_bf16 v[66:69], v[146:149], v[174:177], v[66:69]
	v_mfma_f32_16x16x32_bf16 v[82:85], v[154:157], v[174:177], v[82:85]
	s_barrier
	s_waitcnt lgkmcnt(3)
	v_mfma_f32_16x16x32_bf16 v[78:81], v[146:149], v[170:173], v[78:81]
	v_mfma_f32_16x16x32_bf16 v[90:93], v[154:157], v[170:173], v[90:93]
	s_waitcnt lgkmcnt(2)
	v_mfma_f32_16x16x32_bf16 v[86:89], v[146:149], v[162:165], v[86:89]
	v_mfma_f32_16x16x32_bf16 v[102:105], v[154:157], v[162:165], v[102:105]
	v_mfma_f32_16x16x32_bf16 v[74:77], v[150:153], v[190:193], v[74:77]
	v_mfma_f32_16x16x32_bf16 v[70:73], v[158:161], v[190:193], v[70:73]
	v_mfma_f32_16x16x32_bf16 v[66:69], v[150:153], v[178:181], v[66:69]
	v_mfma_f32_16x16x32_bf16 v[82:85], v[158:161], v[178:181], v[82:85]
	s_waitcnt lgkmcnt(1)
	v_mfma_f32_16x16x32_bf16 v[78:81], v[150:153], v[182:185], v[78:81]
	v_mfma_f32_16x16x32_bf16 v[90:93], v[158:161], v[182:185], v[90:93]
	s_waitcnt lgkmcnt(0)
	v_mfma_f32_16x16x32_bf16 v[86:89], v[150:153], v[166:169], v[86:89]
	v_mfma_f32_16x16x32_bf16 v[102:105], v[158:161], v[166:169], v[102:105]
	s_setprio 0
	s_setprio 1
	v_mfma_f32_16x16x32_bf16 v[98:101], v[130:133], v[186:189], v[98:101]
	v_mfma_f32_16x16x32_bf16 v[94:97], v[138:141], v[186:189], v[94:97]
	v_mfma_f32_16x16x32_bf16 v[106:109], v[130:133], v[174:177], v[106:109]
	v_mfma_f32_16x16x32_bf16 v[110:113], v[138:141], v[174:177], v[110:113]
	v_mfma_f32_16x16x32_bf16 v[114:117], v[130:133], v[170:173], v[114:117]
	v_mfma_f32_16x16x32_bf16 v[118:121], v[138:141], v[170:173], v[118:121]
	v_mfma_f32_16x16x32_bf16 v[122:125], v[130:133], v[162:165], v[122:125]
	v_mfma_f32_16x16x32_bf16 v[126:129], v[138:141], v[162:165], v[126:129]
	v_mfma_f32_16x16x32_bf16 v[98:101], v[134:137], v[190:193], v[98:101]
	v_mfma_f32_16x16x32_bf16 v[94:97], v[142:145], v[190:193], v[94:97]
	v_mfma_f32_16x16x32_bf16 v[106:109], v[134:137], v[178:181], v[106:109]
	v_mfma_f32_16x16x32_bf16 v[110:113], v[142:145], v[178:181], v[110:113]
	v_mfma_f32_16x16x32_bf16 v[114:117], v[134:137], v[182:185], v[114:117]
	v_mfma_f32_16x16x32_bf16 v[118:121], v[142:145], v[182:185], v[118:121]
	v_mfma_f32_16x16x32_bf16 v[122:125], v[134:137], v[166:169], v[122:125]
	v_mfma_f32_16x16x32_bf16 v[126:129], v[142:145], v[166:169], v[126:129]
	s_setprio 0
	s_barrier
	s_mov_b32 m0, s53
	s_mov_b32 s8, s70
	ds_read_b128 v[186:189], v247 offset:49152
	ds_read_b128 v[174:177], v247 offset:51200
	ds_read_b128 v[190:193], v248 offset:49152
	ds_read_b128 v[178:181], v248 offset:51200
	ds_read_b128 v[170:173], v247 offset:53248
	ds_read_b128 v[162:165], v247 offset:55296
	ds_read_b128 v[182:185], v248 offset:53248
	ds_read_b128 v[166:169], v248 offset:55296
	buffer_load_dwordx4 v231, s[8:11], s3 offen lds
	s_mov_b32 m0, s54
	s_and_b64 vcc, exec, s[0:1]
	buffer_load_dwordx4 v234, s[8:11], s3 offen lds
	s_add_i32 s3, s46, 0x100180
	s_mov_b32 m0, s57
	s_nop 0
	buffer_load_dwordx4 v231, s[8:11], s3 offen lds
	s_mov_b32 m0, s58
	s_nop 0
	buffer_load_dwordx4 v234, s[8:11], s3 offen lds
	s_mov_b32 m0, s55
	s_nop 0
	buffer_load_dwordx4 v230, s[8:11], s2 offen lds
	s_mov_b32 m0, s56
	s_nop 0
	buffer_load_dwordx4 v233, s[8:11], s2 offen lds
	s_mov_b64 s[2:3], -1
	s_cbranch_vccz .LBB0_1242
	s_waitcnt vmcnt(8)
	s_mov_b64 s[2:3], 0
